# attention A/B/C epilogues: 8 gate loads issued together with counted waits instead of load-wait-store chains
# speedup vs baseline: 1.0339x; 1.0034x over previous
; #define AP_GLOAD_K(j, t) do { const char* kt_ = (const char*)Kb + (size_t)AP_CL(t) * 64 * kpitch * 2; \
;     _Pragma("unroll") for (int i_ = 0; i_ < KPT; ++i_) { if (i_ + 1 < KPT || kact1) kreg[j][i_] = *(const u32x4*)(kt_ + kgo[i_]); } } while (0)
; #define AP_GLOAD_V(j, t) do { const char* vt_ = (const char*)Vb + (size_t)AP_CL(t) * 64 * vpitch * 2; \
;     _Pragma("unroll") for (int i_ = 0; i_ < VPT; ++i_) vreg[j][i_] = *(const u32x4*)(vt_ + vgo[i_]); } while (0)
; template <int KW, int DQK, int DV>
; DI void attn_dense_pair(LAS unsigned char* lds, const int tid, const bf16_t* Qw, int qpitch, const bf16_t* Kb, int kpitch, const bf16_t* Vb, int vpitch,
;                         float nbound, f32x16 (&o)[DV / 32], float& l_out) {
;     ...
;     for (int t = 1; t + 1 < NT; t += 2) {
;         AP_GLOAD_K(0, t + 2); AP_GLOAD_K(1, t + 3); AP_GLOAD_V(0, t + 1); AP_GLOAD_V(1, t + 2);
;         f32x16 pn0, pn1;
;         __builtin_amdgcn_sched_barrier(0);
;         tile_step<DQK, KP, DV, VP, true, 4, true>(pw, pn0, pn1, cvec, ls, o, qf, lds + (t & 3) * KT + koff, lds + ((t - 1) & 3) * VT + voff, &osum, onesf);
;         __builtin_amdgcn_sched_barrier(0);
;         tile_step<DQK, KP, DV, VP, true, 4, true>(pw, pn0, pn1, cvec, ls, o, qf, lds + ((t + 1) & 3) * KT + koff, lds + (t & 3) * VT + voff, &osum, onesf);
.LBB0_383:
	s_add_i32 s9, s34, 1
	s_add_i32 s8, s34, 2
	s_add_i32 s29, s34, -1
	s_add_i32 s14, s6, 0x8000
	s_cmpk_lt_u32 s34, 0x7d
	s_cselect_b64 s[0:1], -1, 0
	s_and_b64 vcc, s[0:1], exec
	v_lshl_add_u64 v[80:81], v[178:179], 0, s[6:7]
	s_cselect_b32 s14, s14, 0xfe000
	v_lshl_add_u64 v[82:83], v[176:177], 0, s[14:15]
	global_load_dwordx4 v[162:165], v[80:81], off
	global_load_dwordx4 v[150:153], v[82:83], off
	v_add_co_u32_e64 v80, s[0:1], s70, v180
	s_nop 1
	v_addc_co_u32_e64 v81, s[0:1], 0, v181, s[0:1]
	global_load_dwordx4 v[154:157], v[180:181], off
	global_load_dwordx4 v[158:161], v[80:81], off
	s_and_b32 s1, s34, 3
	s_mul_i32 s0, s1, 0x2400
	v_add_u32_e32 v175, s0, v183
	ds_read_b128 v[80:83], v175
	ds_read_b128 v[194:197], v175 offset:32
	ds_read_b128 v[198:201], v175 offset:4608
	ds_read_b128 v[202:205], v175 offset:4640
	s_and_b32 s0, s29, 3
	s_mul_i32 s14, s0, 0x3000
	v_add_u32_e32 v186, s14, v185
	ds_read_b128 v[206:209], v175 offset:64
	ds_read_b64_tr_b16 v[222:223], v186 offset:36864
	ds_read_b64_tr_b16 v[224:225], v186 offset:38400
	s_waitcnt lgkmcnt(6)
	v_mfma_f32_32x32x16_bf16 v[96:111], v[80:83], v[130:133], v[64:79]
	s_waitcnt lgkmcnt(4)
	v_mfma_f32_32x32x16_bf16 v[80:95], v[198:201], v[130:133], v[64:79]
	ds_read_b128 v[198:201], v175 offset:4672
	ds_read_b64_tr_b16 v[226:227], v186 offset:36928
	ds_read_b64_tr_b16 v[228:229], v186 offset:38464
	v_mfma_f32_32x32x16_bf16 v[48:63], v[112:115], v[146:149], v[48:63]
	v_mfma_f32_32x32x16_bf16 v[96:111], v[194:197], v[124:127], v[96:111]
	ds_read_b128 v[194:197], v175 offset:96
	ds_read_b64_tr_b16 v[230:231], v186 offset:39936
	ds_read_b64_tr_b16 v[232:233], v186 offset:41472
	s_waitcnt lgkmcnt(9)
	v_mfma_f32_32x32x16_bf16 v[80:95], v[202:205], v[124:127], v[80:95]
	ds_read_b128 v[202:205], v175 offset:4704
	ds_read_b64_tr_b16 v[234:235], v186 offset:40000
	ds_read_b64_tr_b16 v[236:237], v186 offset:41536
	v_mfma_f32_32x32x16_bf16 v[48:63], v[112:115], v[142:145], v[48:63]
	s_waitcnt lgkmcnt(11)
	v_mfma_f32_32x32x16_bf16 v[96:111], v[206:209], v[120:123], v[96:111]
	ds_read_b64_tr_b16 v[206:207], v186 offset:43008
	ds_read_b64_tr_b16 v[208:209], v186 offset:44544
	s_waitcnt lgkmcnt(10)
	v_mfma_f32_32x32x16_bf16 v[80:95], v[198:201], v[120:123], v[80:95]
	ds_read_b64_tr_b16 v[198:199], v186 offset:43072
	ds_read_b64_tr_b16 v[200:201], v186 offset:44608
	v_mfma_f32_32x32x16_bf16 v[48:63], v[112:115], v[138:141], v[48:63]
	s_waitcnt lgkmcnt(9)
	v_mfma_f32_32x32x16_bf16 v[96:111], v[194:197], v[116:119], v[96:111]
	ds_read_b64_tr_b16 v[194:195], v186 offset:46080
	ds_read_b64_tr_b16 v[196:197], v186 offset:47616
	s_waitcnt lgkmcnt(8)
	v_mfma_f32_32x32x16_bf16 v[80:95], v[202:205], v[116:119], v[80:95]
	ds_read_b64_tr_b16 v[202:203], v186 offset:46144
	ds_read_b64_tr_b16 v[204:205], v186 offset:47680
	v_mfma_f32_32x32x16_bf16 v[48:63], v[112:115], v[134:137], v[48:63]
	v_mfma_f32_32x32x16_bf16 v[32:47], v[222:225], v[146:149], v[32:47]
	s_nop 3
	v_exp_f32_e32 v96, v96
	v_exp_f32_e32 v97, v97
	v_exp_f32_e32 v98, v98
	v_exp_f32_e32 v99, v99
	v_mfma_f32_32x32x16_bf16 v[16:31], v[226:229], v[146:149], v[16:31]
	v_exp_f32_e32 v100, v100
	v_exp_f32_e32 v101, v101
	v_exp_f32_e32 v102, v102
	v_exp_f32_e32 v103, v103
	v_mfma_f32_32x32x16_bf16 v[32:47], v[230:233], v[142:145], v[32:47]
	v_exp_f32_e32 v104, v104
	v_exp_f32_e32 v105, v105
	v_exp_f32_e32 v106, v106
	v_exp_f32_e32 v107, v107
	s_waitcnt lgkmcnt(8)
	v_mfma_f32_32x32x16_bf16 v[16:31], v[234:237], v[142:145], v[16:31]
	v_exp_f32_e32 v108, v108
	v_exp_f32_e32 v109, v109
	v_exp_f32_e32 v110, v110
	v_exp_f32_e32 v111, v111
	s_waitcnt lgkmcnt(6)
	v_mfma_f32_32x32x16_bf16 v[32:47], v[206:209], v[138:141], v[32:47]
	v_exp_f32_e32 v80, v80
	v_exp_f32_e32 v81, v81
	v_exp_f32_e32 v82, v82
	v_exp_f32_e32 v83, v83
	s_waitcnt lgkmcnt(4)
	v_mfma_f32_32x32x16_bf16 v[16:31], v[198:201], v[138:141], v[16:31]
	v_exp_f32_e32 v84, v84
	v_exp_f32_e32 v85, v85
	v_exp_f32_e32 v86, v86
	v_exp_f32_e32 v87, v87
	s_waitcnt lgkmcnt(2)
	v_mfma_f32_32x32x16_bf16 v[32:47], v[194:197], v[134:137], v[32:47]
	v_exp_f32_e32 v88, v88
	v_exp_f32_e32 v89, v89
	v_exp_f32_e32 v90, v90
	v_exp_f32_e32 v91, v91
	s_waitcnt lgkmcnt(0)
	v_mfma_f32_32x32x16_bf16 v[16:31], v[202:205], v[134:137], v[16:31]
	v_cvt_pk_bf16_f32 v135, v90, v91
	v_cvt_pk_bf16_f32 v134, v88, v89
	v_cvt_pk_bf16_f32 v141, v86, v87
	v_cvt_pk_bf16_f32 v140, v84, v85
	v_cvt_pk_bf16_f32 v139, v82, v83
	v_cvt_pk_bf16_f32 v138, v80, v81
	v_cvt_pk_bf16_f32 v145, v110, v111
	v_cvt_pk_bf16_f32 v144, v108, v109
	v_cvt_pk_bf16_f32 v143, v106, v107
	v_cvt_pk_bf16_f32 v142, v104, v105
	v_cvt_pk_bf16_f32 v149, v102, v103
	v_cvt_pk_bf16_f32 v148, v100, v101
	v_cvt_pk_bf16_f32 v147, v98, v99
	v_cvt_pk_bf16_f32 v146, v96, v97
	v_exp_f32_e32 v92, v92
	v_exp_f32_e32 v93, v93
	v_exp_f32_e32 v94, v94
	v_exp_f32_e32 v95, v95
	v_cvt_pk_bf16_f32 v136, v92, v93
	v_cvt_pk_bf16_f32 v137, v94, v95
	s_and_b32 s9, s9, 3
	s_mul_i32 s14, s9, 0x2400
	v_add_u32_e32 v175, s14, v183
	ds_read_b128 v[80:83], v175
	ds_read_b128 v[194:197], v175 offset:32
	ds_read_b128 v[198:201], v175 offset:4608
	ds_read_b128 v[202:205], v175 offset:4640
	s_mulk_i32 s1, 0x3000
	v_add_u32_e32 v186, s1, v185
	ds_read_b128 v[206:209], v175 offset:64
	ds_read_b64_tr_b16 v[222:223], v186 offset:36864
	ds_read_b64_tr_b16 v[224:225], v186 offset:38400
	s_waitcnt lgkmcnt(6)
	v_mfma_f32_32x32x16_bf16 v[96:111], v[80:83], v[130:133], v[64:79]
	s_waitcnt lgkmcnt(4)
; #define AP_LSTORE_K(j, t) do { \
;     _Pragma("unroll") for (int i_ = 0; i_ < KPT; ++i_) { if (i_ + 1 < KPT || kact1) *(LAS u32x4*)(lds + ((t) & 3) * KT + klo[i_]) = kreg[j][i_]; } } while (0)
; #define AP_LSTORE_V(j, t) do { \
;     _Pragma("unroll") for (int i_ = 0; i_ < VPT; ++i_) *(LAS u32x4*)(lds + ((t) & 3) * VT + vlo[i_]) = vreg[j][i_]; } while (0)
; template <int KW, int DQK, int DV>
; DI void attn_dense_pair(LAS unsigned char* lds, const int tid, const bf16_t* Qw, int qpitch, const bf16_t* Kb, int kpitch, const bf16_t* Vb, int vpitch,
;                         float nbound, f32x16 (&o)[DV / 32], float& l_out) {
;     ...
;         tile_step<DQK, KP, DV, VP, true, 4, true>(pw, pn0, pn1, cvec, ls, o, qf, lds + ((t + 1) & 3) * KT + koff, lds + (t & 3) * VT + voff, &osum, onesf);
;         AP_LSTORE_K(0, t + 2); AP_LSTORE_K(1, t + 3); AP_LSTORE_V(0, t + 1); AP_LSTORE_V(1, t + 2);
;         __syncthreads();
	v_mfma_f32_32x32x16_bf16 v[80:95], v[198:201], v[130:133], v[64:79]
	ds_read_b128 v[198:201], v175 offset:4672
	ds_read_b64_tr_b16 v[226:227], v186 offset:36928
	ds_read_b64_tr_b16 v[228:229], v186 offset:38464
	v_mfma_f32_32x32x16_bf16 v[48:63], v[112:115], v[146:149], v[48:63]
	v_mfma_f32_32x32x16_bf16 v[96:111], v[194:197], v[124:127], v[96:111]
	ds_read_b128 v[194:197], v175 offset:96
	ds_read_b64_tr_b16 v[230:231], v186 offset:39936
	ds_read_b64_tr_b16 v[232:233], v186 offset:41472
	s_waitcnt lgkmcnt(9)
	v_mfma_f32_32x32x16_bf16 v[80:95], v[202:205], v[124:127], v[80:95]
	ds_read_b128 v[202:205], v175 offset:4704
	ds_read_b64_tr_b16 v[234:235], v186 offset:40000
	ds_read_b64_tr_b16 v[236:237], v186 offset:41536
	v_mfma_f32_32x32x16_bf16 v[48:63], v[112:115], v[142:145], v[48:63]
	s_waitcnt lgkmcnt(11)
	v_mfma_f32_32x32x16_bf16 v[96:111], v[206:209], v[120:123], v[96:111]
	ds_read_b64_tr_b16 v[206:207], v186 offset:43008
	ds_read_b64_tr_b16 v[208:209], v186 offset:44544
	s_waitcnt lgkmcnt(10)
	v_mfma_f32_32x32x16_bf16 v[80:95], v[198:201], v[120:123], v[80:95]
	ds_read_b64_tr_b16 v[198:199], v186 offset:43072
	ds_read_b64_tr_b16 v[200:201], v186 offset:44608
	v_mfma_f32_32x32x16_bf16 v[48:63], v[112:115], v[138:141], v[48:63]
	s_waitcnt lgkmcnt(9)
	v_mfma_f32_32x32x16_bf16 v[96:111], v[194:197], v[116:119], v[96:111]
	ds_read_b64_tr_b16 v[194:195], v186 offset:46080
	ds_read_b64_tr_b16 v[196:197], v186 offset:47616
	s_waitcnt lgkmcnt(8)
	v_mfma_f32_32x32x16_bf16 v[80:95], v[202:205], v[116:119], v[80:95]
	ds_read_b64_tr_b16 v[202:203], v186 offset:46144
	ds_read_b64_tr_b16 v[204:205], v186 offset:47680
	v_mfma_f32_32x32x16_bf16 v[48:63], v[112:115], v[134:137], v[48:63]
	v_mfma_f32_32x32x16_bf16 v[32:47], v[222:225], v[146:149], v[32:47]
	s_nop 3
	v_exp_f32_e32 v96, v96
	v_exp_f32_e32 v97, v97
	v_exp_f32_e32 v98, v98
	v_exp_f32_e32 v99, v99
	v_mfma_f32_32x32x16_bf16 v[16:31], v[226:229], v[146:149], v[16:31]
	v_exp_f32_e32 v100, v100
	v_exp_f32_e32 v101, v101
	v_exp_f32_e32 v102, v102
	v_exp_f32_e32 v103, v103
	v_mfma_f32_32x32x16_bf16 v[32:47], v[230:233], v[142:145], v[32:47]
	v_exp_f32_e32 v104, v104
	v_exp_f32_e32 v105, v105
	v_exp_f32_e32 v106, v106
	v_exp_f32_e32 v107, v107
	s_waitcnt lgkmcnt(8)
	v_mfma_f32_32x32x16_bf16 v[16:31], v[234:237], v[142:145], v[16:31]
	v_exp_f32_e32 v108, v108
	v_exp_f32_e32 v109, v109
	v_exp_f32_e32 v110, v110
	v_exp_f32_e32 v111, v111
	s_waitcnt lgkmcnt(6)
	v_mfma_f32_32x32x16_bf16 v[32:47], v[206:209], v[138:141], v[32:47]
	v_exp_f32_e32 v80, v80
	v_exp_f32_e32 v81, v81
	v_exp_f32_e32 v82, v82
	v_exp_f32_e32 v83, v83
	s_waitcnt lgkmcnt(4)
	v_mfma_f32_32x32x16_bf16 v[16:31], v[198:201], v[138:141], v[16:31]
	v_exp_f32_e32 v84, v84
	v_exp_f32_e32 v85, v85
	v_exp_f32_e32 v86, v86
	v_exp_f32_e32 v87, v87
	s_waitcnt lgkmcnt(2)
	v_mfma_f32_32x32x16_bf16 v[32:47], v[194:197], v[134:137], v[32:47]
	v_exp_f32_e32 v88, v88
	v_exp_f32_e32 v89, v89
	v_exp_f32_e32 v90, v90
	v_exp_f32_e32 v91, v91
	s_waitcnt lgkmcnt(0)
	v_mfma_f32_32x32x16_bf16 v[16:31], v[202:205], v[134:137], v[16:31]
	v_cvt_pk_bf16_f32 v135, v90, v91
	v_cvt_pk_bf16_f32 v134, v88, v89
	v_cvt_pk_bf16_f32 v141, v86, v87
	v_cvt_pk_bf16_f32 v140, v84, v85
	v_cvt_pk_bf16_f32 v139, v82, v83
	v_cvt_pk_bf16_f32 v138, v80, v81
	v_cvt_pk_bf16_f32 v145, v110, v111
	v_cvt_pk_bf16_f32 v144, v108, v109
	v_cvt_pk_bf16_f32 v143, v106, v107
	v_cvt_pk_bf16_f32 v142, v104, v105
	v_cvt_pk_bf16_f32 v149, v102, v103
	v_cvt_pk_bf16_f32 v148, v100, v101
	v_cvt_pk_bf16_f32 v147, v98, v99
	v_cvt_pk_bf16_f32 v146, v96, v97
	v_exp_f32_e32 v92, v92
	v_exp_f32_e32 v93, v93
	v_exp_f32_e32 v94, v94
	v_exp_f32_e32 v95, v95
	s_and_b32 s1, s8, 3
	s_mul_i32 s14, s1, 0x2400
	v_add_u32_e32 v80, s14, v182
	s_mulk_i32 s0, 0x2400
	s_waitcnt vmcnt(3)
	ds_write_b128 v80, v[162:165]
	v_add_u32_e32 v80, s0, v182
	s_mulk_i32 s9, 0x3000
	s_waitcnt vmcnt(2)
	ds_write_b128 v80, v[150:153]
	v_add_u32_e32 v80, s9, v184
	s_mulk_i32 s1, 0x3000
	s_waitcnt vmcnt(1)
	ds_write_b128 v80, v[154:157] offset:36864
	v_add_u32_e32 v80, s1, v184
	s_mov_b64 s[0:1], 0x460000
	s_add_u32 s6, s6, 0x4000
	v_cvt_pk_bf16_f32 v136, v92, v93
	v_cvt_pk_bf16_f32 v137, v94, v95
	v_lshl_add_u64 v[180:181], v[180:181], 0, s[0:1]
	s_addc_u32 s7, s7, 0
	s_mov_b32 s34, s8
	s_waitcnt vmcnt(0)
	ds_write_b128 v80, v[158:161] offset:36864
	s_waitcnt lgkmcnt(0)
	s_barrier
	s_cbranch_vccnz .LBB0_383
; template <int KW, int DQK, int DV, int MODE> ...
;     ...
;     pv_tile<DV, VP>(o, pw, lds + ((NT - 1) & 1) * VT + voff);
; template <int KW, int DQK, int DV>
; DI void attn_dense_pair(LAS unsigned char* lds, const int tid, const bf16_t* Qw, int qpitch, const bf16_t* Kb, int kpitch, const bf16_t* Vb, int vpitch,
;                         float nbound, f32x16 (&o)[DV / 32], float& l_out) {
;     ...
;     { f32x16 pn0, pn1;
;       tile_step<DQK, KP, DV, VP, true, 4, true>(pw, pn0, pn1, cvec, ls, o, qf, lds + ((NT - 1) & 3) * KT + koff, lds + ((NT - 2) & 3) * VT + voff, &osum, onesf); }
;     rowsum_pw(pw, ls);
;     pv_tile<DV, VP>(o, pw, lds + ((NT - 1) & 3) * VT + voff);
;     float l = (ls[0] + ls[1]) + (ls[2] + ls[3]);
;     __syncthreads();
	ds_read_b128 v[96:99], v183 offset:27648
	ds_read_b128 v[100:103], v183 offset:27680
	ds_read_b128 v[104:107], v183 offset:32256
	ds_read_b128 v[108:111], v183 offset:32288
	s_waitcnt lgkmcnt(3)
	v_mfma_f32_32x32x16_bf16 v[80:95], v[96:99], v[130:133], v[64:79]
	ds_read_b128 v[96:99], v183 offset:27712
	ds_read_b64_tr_b16 v[150:151], v185 offset:61440
	ds_read_b64_tr_b16 v[152:153], v185 offset:62976
	s_waitcnt lgkmcnt(4)
	v_mfma_f32_32x32x16_bf16 v[64:79], v[104:107], v[130:133], v[64:79]
	ds_read_b128 v[104:107], v183 offset:32320
	ds_read_b64_tr_b16 v[130:131], v185 offset:61504
	ds_read_b64_tr_b16 v[132:133], v185 offset:63040
	v_mfma_f32_32x32x16_bf16 v[48:63], v[112:115], v[146:149], v[48:63]
	v_mfma_f32_32x32x16_bf16 v[80:95], v[100:103], v[124:127], v[80:95]
	ds_read_b128 v[100:103], v183 offset:27744
	ds_read_b64_tr_b16 v[154:155], v185 offset:64512
	ds_read_b64_tr_b16 v[156:157], v190 offset:4608
	s_waitcnt lgkmcnt(9)
	v_mfma_f32_32x32x16_bf16 v[64:79], v[108:111], v[124:127], v[64:79]
	ds_read_b128 v[108:111], v183 offset:32352
	ds_read_b64_tr_b16 v[124:125], v185 offset:64576
	ds_read_b64_tr_b16 v[126:127], v190 offset:4672
	v_mfma_f32_32x32x16_bf16 v[48:63], v[112:115], v[142:145], v[48:63]
	s_waitcnt lgkmcnt(11)
	v_mfma_f32_32x32x16_bf16 v[80:95], v[96:99], v[120:123], v[80:95]
	ds_read_b64_tr_b16 v[96:97], v190 offset:6144
	ds_read_b64_tr_b16 v[98:99], v190 offset:7680
	s_waitcnt lgkmcnt(10)
	v_mfma_f32_32x32x16_bf16 v[64:79], v[104:107], v[120:123], v[64:79]
	ds_read_b64_tr_b16 v[104:105], v190 offset:6208
	ds_read_b64_tr_b16 v[106:107], v190 offset:7744
	v_mfma_f32_32x32x16_bf16 v[48:63], v[112:115], v[138:141], v[48:63]
	s_waitcnt lgkmcnt(9)
	v_mfma_f32_32x32x16_bf16 v[80:95], v[100:103], v[116:119], v[80:95]
	ds_read_b64_tr_b16 v[100:101], v190 offset:9216
	ds_read_b64_tr_b16 v[102:103], v190 offset:10752
	s_waitcnt lgkmcnt(8)
	v_mfma_f32_32x32x16_bf16 v[64:79], v[108:111], v[116:119], v[64:79]
	ds_read_b64_tr_b16 v[108:109], v190 offset:9280
	ds_read_b64_tr_b16 v[110:111], v190 offset:10816
	v_mfma_f32_32x32x16_bf16 v[48:63], v[112:115], v[134:137], v[48:63]
	v_mfma_f32_32x32x16_bf16 v[32:47], v[150:153], v[146:149], v[32:47]
	s_nop 10
	v_exp_f32_e32 v49, v80
	v_exp_f32_e32 v52, v81
	v_exp_f32_e32 v53, v82
	v_exp_f32_e32 v62, v83
	v_mfma_f32_32x32x16_bf16 v[16:31], v[130:133], v[146:149], v[16:31]
	v_exp_f32_e32 v63, v84
	v_exp_f32_e32 v80, v85
	v_exp_f32_e32 v81, v86
	v_exp_f32_e32 v82, v87
	v_mfma_f32_32x32x16_bf16 v[32:47], v[154:157], v[142:145], v[32:47]
	v_exp_f32_e32 v58, v88
	v_exp_f32_e32 v83, v89
	v_exp_f32_e32 v59, v90
	v_exp_f32_e32 v84, v91
	s_waitcnt lgkmcnt(8)
	v_mfma_f32_32x32x16_bf16 v[16:31], v[124:127], v[142:145], v[16:31]
	v_exp_f32_e32 v60, v92
	v_exp_f32_e32 v85, v93
	v_exp_f32_e32 v61, v94
	v_exp_f32_e32 v86, v95
	s_waitcnt lgkmcnt(6)
	v_mfma_f32_32x32x16_bf16 v[32:47], v[96:99], v[138:141], v[32:47]
	v_exp_f32_e32 v54, v64
	v_exp_f32_e32 v64, v65
	v_exp_f32_e32 v55, v66
	v_exp_f32_e32 v65, v67
	s_waitcnt lgkmcnt(4)
	v_mfma_f32_32x32x16_bf16 v[16:31], v[104:107], v[138:141], v[16:31]
	v_exp_f32_e32 v56, v68
	v_exp_f32_e32 v66, v69
	v_exp_f32_e32 v57, v70
	v_exp_f32_e32 v67, v71
	s_waitcnt lgkmcnt(2)
	v_mfma_f32_32x32x16_bf16 v[32:47], v[100:103], v[134:137], v[32:47]
	v_exp_f32_e32 v50, v72
	v_exp_f32_e32 v68, v73
	v_exp_f32_e32 v51, v74
	v_exp_f32_e32 v69, v75
	s_waitcnt lgkmcnt(0)
	v_mfma_f32_32x32x16_bf16 v[16:31], v[108:111], v[134:137], v[16:31]
	v_exp_f32_e32 v101, v76
	v_exp_f32_e32 v106, v77
	v_exp_f32_e32 v107, v78
	v_exp_f32_e32 v108, v79
	v_cvt_pk_bf16_f32 v51, v51, v69
	v_cvt_pk_bf16_f32 v50, v50, v68
	v_cvt_pk_bf16_f32 v57, v57, v67
	v_cvt_pk_bf16_f32 v56, v56, v66
	v_cvt_pk_bf16_f32 v55, v55, v65
	v_cvt_pk_bf16_f32 v54, v54, v64
	v_cvt_pk_bf16_f32 v61, v61, v86
	v_cvt_pk_bf16_f32 v60, v60, v85
	v_cvt_pk_bf16_f32 v59, v59, v84
	v_cvt_pk_bf16_f32 v58, v58, v83
	v_cvt_pk_bf16_f32 v69, v81, v82
	v_cvt_pk_bf16_f32 v68, v63, v80
	v_cvt_pk_bf16_f32 v67, v53, v62
	v_cvt_pk_bf16_f32 v66, v49, v52
	v_mov_b32_e32 v49, v252
	s_mov_b32 s0, s20
	ds_read_b64_tr_b16 v[76:77], v193 offset:36864
	ds_read_b64_tr_b16 v[78:79], v193 offset:38400
	ds_read_b64_tr_b16 v[82:83], v193 offset:38464
	ds_read_b64_tr_b16 v[80:81], v193 offset:36928
	ds_read_b64_tr_b16 v[84:85], v193 offset:39936
	ds_read_b64_tr_b16 v[86:87], v193 offset:41472
	ds_read_b64_tr_b16 v[90:91], v193 offset:41536
	ds_read_b64_tr_b16 v[88:89], v193 offset:40000
	ds_read_b64_tr_b16 v[92:93], v193 offset:43008
	ds_read_b64_tr_b16 v[94:95], v193 offset:44544
	ds_read_b64_tr_b16 v[72:73], v193 offset:44608
	ds_read_b64_tr_b16 v[70:71], v193 offset:43072
	ds_read_b64_tr_b16 v[96:97], v193 offset:46080
	ds_read_b64_tr_b16 v[98:99], v193 offset:47616
	ds_read_b64_tr_b16 v[64:65], v193 offset:47680
	ds_read_b64_tr_b16 v[62:63], v193 offset:46144
	s_waitcnt lgkmcnt(0)
	s_barrier
; DI float bflo(unsigned u) { return __uint_as_float(u << 16); }
; DI float bfhi(unsigned u) { return __uint_as_float(u & 0xffff0000u); }
; DI float shx(float v, int m, int lane) { return __int_as_float(__builtin_amdgcn_ds_bpermute((lane ^ m) << 2, __float_as_int(v))); }
; template <int KW, int DQK, int DV>
; DI void attn_dense_pair(LAS unsigned char* lds, const int tid, const bf16_t* Qw, int qpitch, const bf16_t* Kb, int kpitch, const bf16_t* Vb, int vpitch,
;                         float nbound, f32x16 (&o)[DV / 32], float& l_out) {
;     ...
;     rowsum_pw(pw, ls);
;     pv_tile<DV, VP>(o, pw, lds + ((NT - 1) & 3) * VT + voff);
;     float l = (ls[0] + ls[1]) + (ls[2] + ls[3]);
;     __syncthreads();
;     ...
;     l += shx(l, 32, lane);
;     l += __int_as_float(__builtin_amdgcn_ds_bpermute((lane & 31) << 2, __float_as_int(osum[0])));
;     l_out = l;
; DI void store_y64(const f32x16 (&o)[2], float linv, bf16_t* Y, const bf16_t* proj, int token, int ycol, int hi) {
; #pragma unroll
;     for (int d0 = 0; d0 < 2; ++d0)
; #pragma unroll
;         for (int g = 0; g < 4; ++g) {
;             const int col = ycol + 32 * d0 + 8 * g + 4 * hi;
;             const u32x2 gv = *(const u32x2*)(proj + (size_t)token * LDP + C_SILU + col);
;             u32x2 w;
;             w.x = cvt_pk(o[d0][4 * g + 0] * linv * bflo(gv.x), o[d0][4 * g + 1] * linv * bfhi(gv.x));
;             w.y = cvt_pk(o[d0][4 * g + 2] * linv * bflo(gv.y), o[d0][4 * g + 3] * linv * bfhi(gv.y));
;             *(u32x2*)(Y + (size_t)token * DM + col) = w;
;         }
; }
	s_lshl_b32 s1, s0, 8
	s_and_b32 s1, s1, 0x1f00
	s_add_i32 s1, s1, s21
	v_and_or_b32 v100, v49, 31, s1
	s_lshl_b32 s0, s0, 1
	v_ashrrev_i32_e32 v49, 3, v49
	s_andn2_b32 s0, s0, 63
	v_and_b32_e32 v49, -4, v49
	v_add_u32_e32 v49, s0, v49
	v_add_u32_e32 v52, 0x200, v49
	v_mov_b64_e32 v[74:75], s[2:3]
	v_mad_i64_i32 v[74:75], s[0:1], v100, s68, v[74:75]
	v_ashrrev_i32_e32 v53, 31, v52
	v_lshl_add_u64 v[74:75], v[74:75], 0, s[88:89]
	v_lshlrev_b64 v[102:103], 1, v[52:53]
	v_lshl_add_u64 v[52:53], v[74:75], 0, v[102:103]
	global_load_dwordx2 v[104:105], v[52:53], off
	global_load_dwordx2 v[150:151], v[52:53], off offset:16
	global_load_dwordx2 v[152:153], v[52:53], off offset:32
	global_load_dwordx2 v[154:155], v[52:53], off offset:48
	global_load_dwordx2 v[156:157], v[52:53], off offset:64
	global_load_dwordx2 v[158:159], v[52:53], off offset:80
	global_load_dwordx2 v[160:161], v[52:53], off offset:96
	global_load_dwordx2 v[162:163], v[52:53], off offset:112
	v_mfma_f32_32x32x16_bf16 v[32:47], v[76:79], v[66:69], v[32:47]
	v_cvt_pk_bf16_f32 v52, v101, v106
	v_cvt_pk_bf16_f32 v53, v107, v108
	v_mov_b32_e32 v106, v129
	v_mov_b32_e32 v108, v129
	v_mov_b32_e32 v107, v129
	v_mov_b32_e32 v109, v129
	v_dot2c_f32_bf16_e32 v106, 0x3f803f80, v66
	v_dot2c_f32_bf16_e32 v108, 0x3f803f80, v67
	v_dot2c_f32_bf16_e32 v107, 0x3f803f80, v68
	v_dot2c_f32_bf16_e32 v109, 0x3f803f80, v69
	v_dot2c_f32_bf16_e32 v106, 0x3f803f80, v58
	v_dot2c_f32_bf16_e32 v108, 0x3f803f80, v59
	v_dot2c_f32_bf16_e32 v107, 0x3f803f80, v60
	v_dot2c_f32_bf16_e32 v109, 0x3f803f80, v61
	v_dot2c_f32_bf16_e32 v106, 0x3f803f80, v54
	v_dot2c_f32_bf16_e32 v108, 0x3f803f80, v55
	v_dot2c_f32_bf16_e32 v107, 0x3f803f80, v56
	v_dot2c_f32_bf16_e32 v109, 0x3f803f80, v57
	v_mfma_f32_32x32x16_bf16 v[32:47], v[84:87], v[58:61], v[32:47]
	v_dot2c_f32_bf16_e32 v106, 0x3f803f80, v50
	v_dot2c_f32_bf16_e32 v108, 0x3f803f80, v51
	v_dot2c_f32_bf16_e32 v107, 0x3f803f80, v52
	v_dot2c_f32_bf16_e32 v109, 0x3f803f80, v53
	ds_bpermute_b32 v48, v192, v48
	v_ashrrev_i32_e32 v101, 31, v100
	s_add_i32 s20, s20, s28
	v_pk_add_f32 v[76:77], v[106:107], v[108:109]
	v_mfma_f32_32x32x16_bf16 v[32:47], v[92:95], v[54:57], v[32:47]
	v_add_f32_e32 v76, v76, v77
	ds_bpermute_b32 v77, v191, v76
	s_cmpk_gt_i32 s20, 0xff
	s_waitcnt lgkmcnt(0)
	v_add_f32_e32 v76, v76, v77
	v_add_f32_e32 v48, v76, v48
	v_div_scale_f32 v76, s[0:1], v48, v48, 1.0
	v_rcp_f32_e32 v77, v76
	v_mfma_f32_32x32x16_bf16 v[32:47], v[96:99], v[50:53], v[32:47]
	v_fma_f32 v78, -v76, v77, 1.0
	v_fmac_f32_e32 v77, v78, v77
	v_div_scale_f32 v78, vcc, 1.0, v48, 1.0
	v_mul_f32_e32 v79, v78, v77
	v_fma_f32 v84, -v76, v79, v78
	v_fmac_f32_e32 v79, v84, v77
	v_fma_f32 v76, -v76, v79, v78
	v_div_fmas_f32 v76, v76, v77, v79
	v_div_fixup_f32 v48, v76, v48, 1.0
	s_nop 2
	v_pk_mul_f32 v[32:33], v[32:33], v[48:49] op_sel_hi:[1,0]
	v_lshlrev_b64 v[76:77], 12, v[100:101]
	v_lshl_add_u64 v[76:77], s[4:5], 0, v[76:77]
	v_mfma_f32_32x32x16_bf16 v[16:31], v[80:83], v[66:69], v[16:31]
	v_mul_f32_e64 v36, v36, v48
	v_mul_f32_e64 v37, v37, v48
	v_mul_f32_e64 v38, v38, v48
	v_mul_f32_e64 v39, v39, v48
	s_waitcnt vmcnt(7)
	v_lshlrev_b32_e32 v78, 16, v104
	v_and_b32_e32 v79, 0xffff0000, v104
	v_pk_mul_f32 v[32:33], v[32:33], v[78:79]
	v_mfma_f32_32x32x16_bf16 v[16:31], v[88:91], v[58:61], v[16:31]
	v_cvt_pk_bf16_f32 v78, v32, v33
	v_mul_f32_e64 v32, v34, v48
	v_mul_f32_e64 v33, v35, v48
	v_lshlrev_b32_e32 v34, 16, v105
	v_and_b32_e32 v35, 0xffff0000, v105
	v_pk_mul_f32 v[32:33], v[32:33], v[34:35]
	v_add_u32_e32 v34, 0x208, v49
	v_cvt_pk_bf16_f32 v79, v32, v33
	v_lshl_add_u64 v[32:33], v[76:77], 0, v[102:103]
	v_ashrrev_i32_e32 v35, 31, v34
	global_store_dwordx2 v[32:33], v[78:79], off
	v_lshl_add_u64 v[34:35], v[34:35], 1, v[74:75]
	v_add_u32_e32 v76, 0x210, v49
	v_ashrrev_i32_e32 v77, 31, v76
	v_lshl_add_u64 v[76:77], v[76:77], 1, v[74:75]
	v_mfma_f32_32x32x16_bf16 v[16:31], v[70:73], v[54:57], v[16:31]
	s_waitcnt vmcnt(7)
; DI float bflo(unsigned u) { return __uint_as_float(u << 16); }
; DI float bfhi(unsigned u) { return __uint_as_float(u & 0xffff0000u); }
; DI void store_y64(const f32x16 (&o)[2], float linv, bf16_t* Y, const bf16_t* proj, int token, int ycol, int hi) {
; #pragma unroll
;     for (int d0 = 0; d0 < 2; ++d0)
; #pragma unroll
;         for (int g = 0; g < 4; ++g) {
;             const int col = ycol + 32 * d0 + 8 * g + 4 * hi;
;             const u32x2 gv = *(const u32x2*)(proj + (size_t)token * LDP + C_SILU + col);
;             u32x2 w;
;             w.x = cvt_pk(o[d0][4 * g + 0] * linv * bflo(gv.x), o[d0][4 * g + 1] * linv * bfhi(gv.x));
;             w.y = cvt_pk(o[d0][4 * g + 2] * linv * bflo(gv.y), o[d0][4 * g + 3] * linv * bfhi(gv.y));
;             *(u32x2*)(Y + (size_t)token * DM + col) = w;
;         }
; }
	v_lshlrev_b32_e32 v66, 16, v150
	v_and_b32_e32 v67, 0xffff0000, v150
	v_lshlrev_b32_e32 v34, 16, v151
	v_and_b32_e32 v35, 0xffff0000, v151
	v_pk_mul_f32 v[36:37], v[36:37], v[66:67]
	v_pk_mul_f32 v[34:35], v[38:39], v[34:35]
	v_cvt_pk_bf16_f32 v36, v36, v37
	v_cvt_pk_bf16_f32 v37, v34, v35
	global_store_dwordx2 v[32:33], v[36:37], off offset:16
	v_pk_mul_f32 v[38:39], v[40:41], v[48:49] op_sel_hi:[1,0]
	v_pk_mul_f32 v[40:41], v[42:43], v[48:49] op_sel_hi:[1,0]
	v_add_u32_e32 v36, 0x218, v49
	v_ashrrev_i32_e32 v37, 31, v36
	v_lshl_add_u64 v[36:37], v[36:37], 1, v[74:75]
	v_mfma_f32_32x32x16_bf16 v[16:31], v[62:65], v[50:53], v[16:31]
	s_waitcnt vmcnt(7)
	v_lshlrev_b32_e32 v42, 16, v152
	v_and_b32_e32 v43, 0xffff0000, v152
	v_lshlrev_b32_e32 v34, 16, v153
	v_and_b32_e32 v35, 0xffff0000, v153
	v_pk_mul_f32 v[38:39], v[38:39], v[42:43]
	v_pk_mul_f32 v[34:35], v[40:41], v[34:35]
	v_cvt_pk_bf16_f32 v38, v38, v39
	v_cvt_pk_bf16_f32 v39, v34, v35
	global_store_dwordx2 v[32:33], v[38:39], off offset:32
	v_pk_mul_f32 v[38:39], v[44:45], v[48:49] op_sel_hi:[1,0]
	v_pk_mul_f32 v[40:41], v[46:47], v[48:49] op_sel_hi:[1,0]
	v_add_u32_e32 v36, 0x220, v49
	v_ashrrev_i32_e32 v37, 31, v36
	v_lshl_add_u64 v[36:37], v[36:37], 1, v[74:75]
	v_pk_mul_f32 v[16:17], v[16:17], v[48:49] op_sel_hi:[1,0]
	v_pk_mul_f32 v[18:19], v[18:19], v[48:49] op_sel_hi:[1,0]
	v_pk_mul_f32 v[20:21], v[20:21], v[48:49] op_sel_hi:[1,0]
	v_pk_mul_f32 v[22:23], v[22:23], v[48:49] op_sel_hi:[1,0]
	s_waitcnt vmcnt(7)
	v_lshlrev_b32_e32 v42, 16, v154
	v_and_b32_e32 v43, 0xffff0000, v154
	v_lshlrev_b32_e32 v34, 16, v155
	v_and_b32_e32 v35, 0xffff0000, v155
	v_pk_mul_f32 v[38:39], v[38:39], v[42:43]
	v_pk_mul_f32 v[34:35], v[40:41], v[34:35]
	v_cvt_pk_bf16_f32 v38, v38, v39
	v_cvt_pk_bf16_f32 v39, v34, v35
	global_store_dwordx2 v[32:33], v[38:39], off offset:48
	v_add_u32_e32 v36, 0x228, v49
	v_ashrrev_i32_e32 v37, 31, v36
	v_lshl_add_u64 v[36:37], v[36:37], 1, v[74:75]
	s_waitcnt vmcnt(7)
	v_lshlrev_b32_e32 v38, 16, v156
	v_and_b32_e32 v39, 0xffff0000, v156
	v_lshlrev_b32_e32 v34, 16, v157
	v_and_b32_e32 v35, 0xffff0000, v157
	v_pk_mul_f32 v[16:17], v[16:17], v[38:39]
	v_pk_mul_f32 v[18:19], v[18:19], v[34:35]
	v_cvt_pk_bf16_f32 v16, v16, v17
	v_cvt_pk_bf16_f32 v17, v18, v19
	global_store_dwordx2 v[32:33], v[16:17], off offset:64
	v_add_u32_e32 v18, 0x230, v49
	v_ashrrev_i32_e32 v19, 31, v18
	v_lshl_add_u64 v[18:19], v[18:19], 1, v[74:75]
	s_waitcnt vmcnt(7)
	v_lshlrev_b32_e32 v34, 16, v158
	v_and_b32_e32 v35, 0xffff0000, v158
	v_lshlrev_b32_e32 v16, 16, v159
	v_and_b32_e32 v17, 0xffff0000, v159
	v_pk_mul_f32 v[20:21], v[20:21], v[34:35]
	v_pk_mul_f32 v[16:17], v[22:23], v[16:17]
	v_cvt_pk_bf16_f32 v20, v20, v21
	v_cvt_pk_bf16_f32 v21, v16, v17
	global_store_dwordx2 v[32:33], v[20:21], off offset:80
	v_pk_mul_f32 v[20:21], v[24:25], v[48:49] op_sel_hi:[1,0]
	v_pk_mul_f32 v[22:23], v[26:27], v[48:49] op_sel_hi:[1,0]
	v_add_u32_e32 v18, 0x238, v49
	v_ashrrev_i32_e32 v19, 31, v18
	v_lshl_add_u64 v[18:19], v[18:19], 1, v[74:75]
	s_waitcnt vmcnt(7)
	v_lshlrev_b32_e32 v24, 16, v160
	v_and_b32_e32 v25, 0xffff0000, v160
	v_lshlrev_b32_e32 v16, 16, v161
	v_and_b32_e32 v17, 0xffff0000, v161
	v_pk_mul_f32 v[20:21], v[20:21], v[24:25]
	v_pk_mul_f32 v[16:17], v[22:23], v[16:17]
	v_cvt_pk_bf16_f32 v20, v20, v21
	v_cvt_pk_bf16_f32 v21, v16, v17
	global_store_dwordx2 v[32:33], v[20:21], off offset:96
	v_pk_mul_f32 v[18:19], v[28:29], v[48:49] op_sel_hi:[1,0]
	v_pk_mul_f32 v[20:21], v[30:31], v[48:49] op_sel_hi:[1,0]
	s_waitcnt vmcnt(7)
	v_lshlrev_b32_e32 v22, 16, v162
	v_and_b32_e32 v23, 0xffff0000, v162
	v_lshlrev_b32_e32 v16, 16, v163
	v_and_b32_e32 v17, 0xffff0000, v163
	v_pk_mul_f32 v[18:19], v[18:19], v[22:23]
	v_pk_mul_f32 v[16:17], v[20:21], v[16:17]
	v_cvt_pk_bf16_f32 v18, v18, v19
	v_cvt_pk_bf16_f32 v19, v16, v17
	global_store_dwordx2 v[32:33], v[18:19], off offset:112
	s_cbranch_scc0 .LBB0_382

; DI float bflo(unsigned u) { return __uint_as_float(u << 16); }
; DI float bfhi(unsigned u) { return __uint_as_float(u & 0xffff0000u); }
; DI float shx(float v, int m, int lane) { return __int_as_float(__builtin_amdgcn_ds_bpermute((lane ^ m) << 2, __float_as_int(v))); }
; #define RELANE(x) int x = (int)__builtin_amdgcn_mbcnt_hi(~0u, __builtin_amdgcn_mbcnt_lo(~0u, 0u)); asm volatile("" : "+v"(x));
; DI void store_y64(const f32x16 (&o)[2], float linv, bf16_t* Y, const bf16_t* proj, int token, int ycol, int hi) {
; #pragma unroll
;     for (int d0 = 0; d0 < 2; ++d0)
; #pragma unroll
;         for (int g = 0; g < 4; ++g) {
;             const int col = ycol + 32 * d0 + 8 * g + 4 * hi;
;             const u32x2 gv = *(const u32x2*)(proj + (size_t)token * LDP + C_SILU + col);
;             u32x2 w;
;             w.x = cvt_pk(o[d0][4 * g + 0] * linv * bflo(gv.x), o[d0][4 * g + 1] * linv * bfhi(gv.x));
;             w.y = cvt_pk(o[d0][4 * g + 2] * linv * bflo(gv.y), o[d0][4 * g + 3] * linv * bfhi(gv.y));
;             *(u32x2*)(Y + (size_t)token * DM + col) = w;
;         }
; }
; __global__ void __launch_bounds__(512) mega(Params P) {
;     ...
;                     { RELANE(l2) lsum += shx(lsum, 32, l2); int u2 = u; asm volatile("" : "+s"(u2)); const int h2 = u2 >> 5, i02 = ((u2 >> 1) & 15) * 32, r162 = (u2 & 1) * 8 + wid;
;                       store_y64(o, 1.0f / lsum, Yb, proj, 16 * (i02 + (l2 & 31)) + r162, 1024 + h2 * 64, l2 >> 5); }
.LBB0_558:
	v_mov_b32_e32 v33, v252
	s_mov_b32 s0, s21
	s_lshl_b32 s1, s0, 4
	s_lshl_b32 s4, s0, 3
	s_and_b32 s1, s1, 0x1e0
	s_and_b32 s4, s4, 8
	s_lshl_b32 s0, s0, 1
	v_ashrrev_i32_e32 v34, 3, v33
	s_add_i32 s4, s4, s20
	v_and_or_b32 v32, v33, 31, s1
	s_andn2_b32 s0, s0, 63
	v_and_b32_e32 v34, -4, v34
	v_lshl_add_u32 v32, v32, 4, s4
	v_add_u32_e32 v44, s0, v34
	v_mov_b64_e32 v[34:35], s[8:9]
	v_add_u32_e32 v36, 0x400, v44
	v_mad_i64_i32 v[34:35], s[0:1], v32, s68, v[34:35]
	s_mov_b64 s[0:1], 0x3b40
	v_ashrrev_i32_e32 v37, 31, v36
	v_lshl_add_u64 v[34:35], v[34:35], 0, s[0:1]
	v_lshlrev_b64 v[36:37], 1, v[36:37]
	v_lshl_add_u64 v[38:39], v[34:35], 0, v[36:37]
	global_load_dwordx2 v[80:81], v[38:39], off offset:16
	global_load_dwordx2 v[82:83], v[38:39], off offset:32
	global_load_dwordx2 v[84:85], v[38:39], off offset:48
	global_load_dwordx2 v[86:87], v[38:39], off offset:64
	global_load_dwordx2 v[88:89], v[38:39], off offset:80
	global_load_dwordx2 v[90:91], v[38:39], off offset:96
	global_load_dwordx2 v[92:93], v[38:39], off offset:112
	global_load_dwordx2 v[38:39], v[38:39], off
	v_pk_add_f32 v[40:41], v[146:147], v[148:149]
	v_lshlrev_b32_e32 v33, 2, v33
	v_add_f32_e32 v42, v40, v41
	v_xor_b32_e32 v33, 0x80, v33
	ds_bpermute_b32 v43, v33, v42
	v_ashrrev_i32_e32 v33, 31, v32
	v_lshlrev_b64 v[32:33], 12, v[32:33]
	v_lshl_add_u64 v[32:33], s[10:11], 0, v[32:33]
	v_lshl_add_u64 v[32:33], v[32:33], 0, v[36:37]
	s_waitcnt lgkmcnt(0)
	v_add_f32_e32 v42, v42, v43
	v_div_scale_f32 v43, s[0:1], v42, v42, 1.0
	v_rcp_f32_e32 v45, v43
	v_div_scale_f32 v36, vcc, 1.0, v42, 1.0
	v_add_u32_e32 v40, 0x408, v44
	v_fma_f32 v37, -v43, v45, 1.0
	v_fmac_f32_e32 v45, v37, v45
	v_mul_f32_e32 v37, v36, v45
	v_fma_f32 v46, -v43, v37, v36
	v_fmac_f32_e32 v37, v46, v45
	v_fma_f32 v36, -v43, v37, v36
	v_div_fmas_f32 v36, v36, v45, v37
	v_div_fixup_f32 v36, v36, v42, 1.0
	v_pk_mul_f32 v[16:17], v[36:37], v[16:17] op_sel_hi:[0,1]
	v_pk_mul_f32 v[18:19], v[36:37], v[18:19] op_sel_hi:[0,1]
	v_ashrrev_i32_e32 v41, 31, v40
	v_lshl_add_u64 v[40:41], v[40:41], 1, v[34:35]
	v_pk_mul_f32 v[20:21], v[36:37], v[20:21] op_sel_hi:[0,1]
	v_pk_mul_f32 v[22:23], v[36:37], v[22:23] op_sel_hi:[0,1]
	v_pk_mul_f32 v[0:1], v[36:37], v[0:1] op_sel_hi:[0,1]
	v_pk_mul_f32 v[2:3], v[36:37], v[2:3] op_sel_hi:[0,1]
	v_pk_mul_f32 v[4:5], v[36:37], v[4:5] op_sel_hi:[0,1]
	v_pk_mul_f32 v[6:7], v[36:37], v[6:7] op_sel_hi:[0,1]
	v_readlane_b32 s0, v254, 20
	s_add_i32 s21, s21, s28
	s_add_i32 s55, s55, s0
	s_add_i32 s57, s57, s38
	s_cmpk_gt_i32 s21, 0xff
	s_waitcnt vmcnt(0)
	v_lshlrev_b32_e32 v42, 16, v38
	v_and_b32_e32 v43, 0xffff0000, v38
	v_lshlrev_b32_e32 v38, 16, v39
	v_and_b32_e32 v39, 0xffff0000, v39
	v_pk_mul_f32 v[16:17], v[16:17], v[42:43]
	v_pk_mul_f32 v[18:19], v[18:19], v[38:39]
	v_cvt_pk_bf16_f32 v16, v16, v17
	v_cvt_pk_bf16_f32 v17, v18, v19
	global_store_dwordx2 v[32:33], v[16:17], off
	v_add_u32_e32 v18, 0x410, v44
	v_ashrrev_i32_e32 v19, 31, v18
	v_lshl_add_u64 v[18:19], v[18:19], 1, v[34:35]
	s_waitcnt vmcnt(7)
	v_lshlrev_b32_e32 v38, 16, v80
	v_and_b32_e32 v39, 0xffff0000, v80
	v_lshlrev_b32_e32 v16, 16, v81
	v_and_b32_e32 v17, 0xffff0000, v81
	v_pk_mul_f32 v[20:21], v[20:21], v[38:39]
	v_pk_mul_f32 v[16:17], v[22:23], v[16:17]
	v_cvt_pk_bf16_f32 v20, v20, v21
	v_cvt_pk_bf16_f32 v21, v16, v17
	global_store_dwordx2 v[32:33], v[20:21], off offset:16
	v_pk_mul_f32 v[20:21], v[36:37], v[24:25] op_sel_hi:[0,1]
	v_pk_mul_f32 v[22:23], v[36:37], v[26:27] op_sel_hi:[0,1]
	v_add_u32_e32 v18, 0x418, v44
	v_ashrrev_i32_e32 v19, 31, v18
	v_lshl_add_u64 v[18:19], v[18:19], 1, v[34:35]
	s_waitcnt vmcnt(7)
	v_lshlrev_b32_e32 v24, 16, v82
	v_and_b32_e32 v25, 0xffff0000, v82
	v_lshlrev_b32_e32 v16, 16, v83
	v_and_b32_e32 v17, 0xffff0000, v83
	v_pk_mul_f32 v[20:21], v[20:21], v[24:25]
	v_pk_mul_f32 v[16:17], v[22:23], v[16:17]
	v_cvt_pk_bf16_f32 v20, v20, v21
	v_cvt_pk_bf16_f32 v21, v16, v17
	global_store_dwordx2 v[32:33], v[20:21], off offset:32
	v_pk_mul_f32 v[20:21], v[36:37], v[28:29] op_sel_hi:[0,1]
	v_pk_mul_f32 v[22:23], v[36:37], v[30:31] op_sel_hi:[0,1]
	v_add_u32_e32 v18, 0x420, v44
	v_ashrrev_i32_e32 v19, 31, v18
	v_lshl_add_u64 v[18:19], v[18:19], 1, v[34:35]
	s_waitcnt vmcnt(7)
	v_lshlrev_b32_e32 v24, 16, v84
	v_and_b32_e32 v25, 0xffff0000, v84
	v_lshlrev_b32_e32 v16, 16, v85
	v_and_b32_e32 v17, 0xffff0000, v85
	v_pk_mul_f32 v[20:21], v[20:21], v[24:25]
	v_pk_mul_f32 v[16:17], v[22:23], v[16:17]
	v_cvt_pk_bf16_f32 v20, v20, v21
	v_cvt_pk_bf16_f32 v21, v16, v17
	global_store_dwordx2 v[32:33], v[20:21], off offset:48
	v_add_u32_e32 v18, 0x428, v44
	v_ashrrev_i32_e32 v19, 31, v18
	v_lshl_add_u64 v[18:19], v[18:19], 1, v[34:35]
	s_waitcnt vmcnt(7)
	v_lshlrev_b32_e32 v20, 16, v86
	v_and_b32_e32 v21, 0xffff0000, v86
	v_lshlrev_b32_e32 v16, 16, v87
	v_and_b32_e32 v17, 0xffff0000, v87
	v_pk_mul_f32 v[0:1], v[0:1], v[20:21]
	v_pk_mul_f32 v[2:3], v[2:3], v[16:17]
	v_cvt_pk_bf16_f32 v0, v0, v1
	v_cvt_pk_bf16_f32 v1, v2, v3
	global_store_dwordx2 v[32:33], v[0:1], off offset:64
	v_add_u32_e32 v2, 0x430, v44
	v_ashrrev_i32_e32 v3, 31, v2
	v_lshl_add_u64 v[2:3], v[2:3], 1, v[34:35]
	s_waitcnt vmcnt(7)
	v_lshlrev_b32_e32 v16, 16, v88
	v_and_b32_e32 v17, 0xffff0000, v88
	v_lshlrev_b32_e32 v0, 16, v89
	v_and_b32_e32 v1, 0xffff0000, v89
	v_pk_mul_f32 v[4:5], v[4:5], v[16:17]
	v_pk_mul_f32 v[0:1], v[6:7], v[0:1]
	v_cvt_pk_bf16_f32 v4, v4, v5
	v_cvt_pk_bf16_f32 v5, v0, v1
	global_store_dwordx2 v[32:33], v[4:5], off offset:80
	v_pk_mul_f32 v[4:5], v[36:37], v[8:9] op_sel_hi:[0,1]
	v_pk_mul_f32 v[6:7], v[36:37], v[10:11] op_sel_hi:[0,1]
	v_add_u32_e32 v2, 0x438, v44
	v_ashrrev_i32_e32 v3, 31, v2
	v_lshl_add_u64 v[2:3], v[2:3], 1, v[34:35]
	s_waitcnt vmcnt(7)
	v_lshlrev_b32_e32 v8, 16, v90
	v_and_b32_e32 v9, 0xffff0000, v90
	v_lshlrev_b32_e32 v0, 16, v91
	v_and_b32_e32 v1, 0xffff0000, v91
	v_pk_mul_f32 v[4:5], v[4:5], v[8:9]
	v_pk_mul_f32 v[0:1], v[6:7], v[0:1]
	v_cvt_pk_bf16_f32 v4, v4, v5
	v_cvt_pk_bf16_f32 v5, v0, v1
	global_store_dwordx2 v[32:33], v[4:5], off offset:96
	v_pk_mul_f32 v[2:3], v[36:37], v[12:13] op_sel_hi:[0,1]
	v_pk_mul_f32 v[4:5], v[36:37], v[14:15] op_sel_hi:[0,1]
	s_waitcnt vmcnt(7)
	v_lshlrev_b32_e32 v6, 16, v92
	v_and_b32_e32 v7, 0xffff0000, v92
	v_lshlrev_b32_e32 v0, 16, v93
	v_and_b32_e32 v1, 0xffff0000, v93
	v_pk_mul_f32 v[2:3], v[2:3], v[6:7]
	v_pk_mul_f32 v[0:1], v[4:5], v[0:1]
	v_cvt_pk_bf16_f32 v2, v2, v3
	v_cvt_pk_bf16_f32 v3, v0, v1
	global_store_dwordx2 v[32:33], v[2:3], off offset:112
	s_cbranch_scc1 .LBB0_585

; DI float bflo(unsigned u) { return __uint_as_float(u << 16); }
; DI float bfhi(unsigned u) { return __uint_as_float(u & 0xffff0000u); }
; DI float shx(float v, int m, int lane) { return __int_as_float(__builtin_amdgcn_ds_bpermute((lane ^ m) << 2, __float_as_int(v))); }
; template <int KW, int DQK, int DV, int MODE> ...
;     ...
;     rowsum_pw(pw, ls);
;     pv_tile<DV, VP>(o, pw, lds + ((NT - 1) & 1) * VT + voff);
;     l = (ls[0] + ls[1]) + (ls[2] + ls[3]);
;     __syncthreads();
;     ...
;     l += shx(l, 32, lane);
;     if (MODE == 0) l += __int_as_float(__builtin_amdgcn_ds_bpermute((lane & 31) << 2, __float_as_int(osum[0])));
;     l_out = l;
; DI void store_y64(const f32x16 (&o)[2], float linv, bf16_t* Y, const bf16_t* proj, int token, int ycol, int hi) {
; #pragma unroll
;     for (int d0 = 0; d0 < 2; ++d0)
; #pragma unroll
;         for (int g = 0; g < 4; ++g) {
;             const int col = ycol + 32 * d0 + 8 * g + 4 * hi;
;             const u32x2 gv = *(const u32x2*)(proj + (size_t)token * LDP + C_SILU + col);
;             u32x2 w;
;             w.x = cvt_pk(o[d0][4 * g + 0] * linv * bflo(gv.x), o[d0][4 * g + 1] * linv * bfhi(gv.x));
;             w.y = cvt_pk(o[d0][4 * g + 2] * linv * bflo(gv.y), o[d0][4 * g + 3] * linv * bfhi(gv.y));
;             *(u32x2*)(Y + (size_t)token * DM + col) = w;
;         }
; }
.LBB0_624:
	s_or_b64 exec, exec, s[6:7]
	v_exp_f32_e32 v48, v48
	v_exp_f32_e32 v49, v49
	v_exp_f32_e32 v50, v50
	v_exp_f32_e32 v51, v51
	v_exp_f32_e32 v52, v52
	v_exp_f32_e32 v53, v53
	v_cvt_pk_bf16_f32 v48, v48, v49
	v_cvt_pk_bf16_f32 v49, v50, v51
	v_exp_f32_e32 v51, v54
	v_cvt_pk_bf16_f32 v50, v52, v53
	v_exp_f32_e32 v52, v55
	v_exp_f32_e32 v53, v88
	v_exp_f32_e32 v54, v89
	v_exp_f32_e32 v55, v90
	v_exp_f32_e32 v88, v91
	v_exp_f32_e32 v89, v92
	v_exp_f32_e32 v90, v93
	v_mov_b32_e32 v92, v252
	s_mov_b32 s6, s20
	v_cvt_pk_bf16_f32 v51, v51, v52
	v_cvt_pk_bf16_f32 v52, v53, v54
	v_cvt_pk_bf16_f32 v53, v55, v88
	v_cvt_pk_bf16_f32 v54, v89, v90
	v_exp_f32_e32 v55, v80
	v_exp_f32_e32 v127, v81
	v_exp_f32_e32 v154, v82
	v_exp_f32_e32 v155, v83
	s_waitcnt vmcnt(0)
	ds_write_b128 v197, v[146:149] offset:38912
	s_waitcnt lgkmcnt(0)
	s_barrier
	ds_read_b64_tr_b16 v[122:123], v198 offset:38912
	ds_read_b64_tr_b16 v[124:125], v198 offset:40448
	ds_read_b64_tr_b16 v[132:133], v198 offset:40512
	ds_read_b64_tr_b16 v[130:131], v198 offset:38976
	ds_read_b64_tr_b16 v[134:135], v198 offset:41984
	ds_read_b64_tr_b16 v[136:137], v198 offset:43520
	ds_read_b64_tr_b16 v[118:119], v198 offset:43584
	ds_read_b64_tr_b16 v[116:117], v198 offset:42048
	ds_read_b64_tr_b16 v[138:139], v198 offset:45056
	ds_read_b64_tr_b16 v[140:141], v198 offset:46592
	ds_read_b64_tr_b16 v[90:91], v198 offset:46656
	ds_read_b64_tr_b16 v[88:89], v198 offset:45120
	ds_read_b64_tr_b16 v[142:143], v198 offset:48128
	ds_read_b64_tr_b16 v[144:145], v198 offset:49664
	ds_read_b64_tr_b16 v[82:83], v198 offset:49728
	ds_read_b64_tr_b16 v[80:81], v198 offset:48192
	s_waitcnt lgkmcnt(0)
	s_barrier
	s_lshl_b32 s7, s6, 8
	s_and_b32 s7, s7, 0x1f00
	s_add_i32 s7, s7, s30
	v_and_or_b32 v126, v92, 31, s7
	s_lshl_b32 s6, s6, 1
	v_ashrrev_i32_e32 v92, 3, v92
	s_andn2_b32 s6, s6, 63
	v_and_b32_e32 v92, -4, v92
	v_add_u32_e32 v92, s6, v92
	v_mov_b64_e32 v[120:121], s[2:3]
	v_mad_i64_i32 v[120:121], s[6:7], v126, s68, v[120:121]
	v_ashrrev_i32_e32 v93, 31, v92
	v_lshl_add_u64 v[120:121], v[120:121], 0, s[88:89]
	v_lshlrev_b64 v[150:151], 1, v[92:93]
	v_lshl_add_u64 v[146:147], v[120:121], 0, v[150:151]
	global_load_dwordx2 v[152:153], v[146:147], off
	global_load_dwordx2 v[156:157], v[146:147], off offset:16
	global_load_dwordx2 v[158:159], v[146:147], off offset:32
	global_load_dwordx2 v[160:161], v[146:147], off offset:48
	global_load_dwordx2 v[162:163], v[146:147], off offset:64
	global_load_dwordx2 v[164:165], v[146:147], off offset:80
	global_load_dwordx2 v[166:167], v[146:147], off offset:96
	global_load_dwordx2 v[168:169], v[146:147], off offset:112
	v_mfma_f32_32x32x16_bf16 v[64:79], v[112:115], v[108:111], v[64:79]
	v_cvt_pk_bf16_f32 v146, v55, v127
	v_exp_f32_e32 v55, v84
	v_exp_f32_e32 v84, v85
	v_exp_f32_e32 v56, v56
	v_exp_f32_e32 v57, v57
	v_exp_f32_e32 v62, v62
	v_cvt_pk_bf16_f32 v148, v55, v84
	v_mfma_f32_32x32x16_bf16 v[64:79], v[112:115], v[104:107], v[64:79]
	v_cvt_pk_bf16_f32 v104, v56, v57
	v_exp_f32_e32 v55, v60
	v_exp_f32_e32 v57, v86
	v_exp_f32_e32 v60, v87
	v_exp_f32_e32 v63, v63
	v_cvt_pk_bf16_f32 v147, v154, v155
	v_exp_f32_e32 v56, v61
	v_mfma_f32_32x32x16_bf16 v[64:79], v[112:115], v[100:103], v[64:79]
	v_cvt_pk_bf16_f32 v149, v57, v60
	v_exp_f32_e32 v58, v58
	v_exp_f32_e32 v59, v59
	v_cvt_pk_bf16_f32 v107, v62, v63
	v_exp_f32_e32 v61, v94
	v_exp_f32_e32 v62, v95
	v_cvt_pk_bf16_f32 v106, v55, v56
	v_mfma_f32_32x32x16_bf16 v[32:47], v[122:125], v[146:149], v[32:47]
	v_cvt_pk_bf16_f32 v105, v58, v59
	v_mov_b32_e32 v56, v129
	v_mov_b32_e32 v58, v129
	v_mov_b32_e32 v57, v129
	v_mov_b32_e32 v59, v129
	v_cvt_pk_bf16_f32 v55, v61, v62
	v_dot2c_f32_bf16_e32 v56, 0x3f803f80, v146
	v_mfma_f32_32x32x16_bf16 v[64:79], v[112:115], v[96:99], v[64:79]
	v_dot2c_f32_bf16_e32 v58, 0x3f803f80, v147
	v_dot2c_f32_bf16_e32 v57, 0x3f803f80, v148
	v_dot2c_f32_bf16_e32 v59, 0x3f803f80, v149
	v_dot2c_f32_bf16_e32 v56, 0x3f803f80, v52
	v_dot2c_f32_bf16_e32 v58, 0x3f803f80, v53
	v_dot2c_f32_bf16_e32 v57, 0x3f803f80, v54
	v_dot2c_f32_bf16_e32 v59, 0x3f803f80, v55
	v_dot2c_f32_bf16_e32 v56, 0x3f803f80, v48
	v_dot2c_f32_bf16_e32 v58, 0x3f803f80, v49
	v_dot2c_f32_bf16_e32 v57, 0x3f803f80, v50
	v_dot2c_f32_bf16_e32 v59, 0x3f803f80, v51
	v_mfma_f32_32x32x16_bf16 v[32:47], v[134:137], v[52:55], v[32:47]
	v_dot2c_f32_bf16_e32 v56, 0x3f803f80, v104
	v_dot2c_f32_bf16_e32 v58, 0x3f803f80, v105
	v_dot2c_f32_bf16_e32 v57, 0x3f803f80, v106
	v_dot2c_f32_bf16_e32 v59, 0x3f803f80, v107
	v_ashrrev_i32_e32 v127, 31, v126
	s_add_i32 s20, s20, s28
	s_cmpk_gt_i32 s20, 0xff
	v_pk_add_f32 v[56:57], v[56:57], v[58:59]
	ds_bpermute_b32 v58, v200, v64
	v_add_f32_e32 v56, v56, v57
	ds_bpermute_b32 v57, v199, v56
	v_mfma_f32_32x32x16_bf16 v[32:47], v[138:141], v[48:51], v[32:47]
	s_waitcnt lgkmcnt(0)
	v_add_f32_e32 v56, v56, v57
	v_add_f32_e32 v56, v56, v58
	v_div_scale_f32 v57, s[6:7], v56, v56, 1.0
	v_rcp_f32_e32 v58, v57
	v_mfma_f32_32x32x16_bf16 v[32:47], v[142:145], v[104:107], v[32:47]
	v_fma_f32 v59, -v57, v58, 1.0
	v_fmac_f32_e32 v58, v59, v58
	v_div_scale_f32 v59, vcc, 1.0, v56, 1.0
	v_mul_f32_e32 v60, v59, v58
	v_fma_f32 v61, -v57, v60, v59
	v_fmac_f32_e32 v60, v61, v58
	v_fma_f32 v57, -v57, v60, v59
	v_div_fmas_f32 v57, v57, v58, v60
	v_div_fixup_f32 v56, v57, v56, 1.0
	s_nop 2
	v_pk_mul_f32 v[32:33], v[32:33], v[56:57] op_sel_hi:[1,0]
	s_waitcnt vmcnt(7)
; DI float bflo(unsigned u) { return __uint_as_float(u << 16); }
; DI float bfhi(unsigned u) { return __uint_as_float(u & 0xffff0000u); }
; DI void store_y64(const f32x16 (&o)[2], float linv, bf16_t* Y, const bf16_t* proj, int token, int ycol, int hi) {
; #pragma unroll
;     for (int d0 = 0; d0 < 2; ++d0)
; #pragma unroll
;         for (int g = 0; g < 4; ++g) {
;             const int col = ycol + 32 * d0 + 8 * g + 4 * hi;
;             const u32x2 gv = *(const u32x2*)(proj + (size_t)token * LDP + C_SILU + col);
;             u32x2 w;
;             w.x = cvt_pk(o[d0][4 * g + 0] * linv * bflo(gv.x), o[d0][4 * g + 1] * linv * bfhi(gv.x));
;             w.y = cvt_pk(o[d0][4 * g + 2] * linv * bflo(gv.y), o[d0][4 * g + 3] * linv * bfhi(gv.y));
;             *(u32x2*)(Y + (size_t)token * DM + col) = w;
;         }
; }
	v_lshlrev_b32_e32 v60, 16, v152
	v_and_b32_e32 v61, 0xffff0000, v152
	v_pk_mul_f32 v[32:33], v[32:33], v[60:61]
	v_lshlrev_b64 v[58:59], 12, v[126:127]
	v_cvt_pk_bf16_f32 v60, v32, v33
	v_pk_mul_f32 v[32:33], v[34:35], v[56:57] op_sel_hi:[1,0]
	v_lshlrev_b32_e32 v34, 16, v153
	v_and_b32_e32 v35, 0xffff0000, v153
	v_lshl_add_u64 v[58:59], s[4:5], 0, v[58:59]
	v_pk_mul_f32 v[32:33], v[32:33], v[34:35]
	v_add_u32_e32 v34, 8, v92
	v_cvt_pk_bf16_f32 v61, v32, v33
	v_lshl_add_u64 v[32:33], v[58:59], 0, v[150:151]
	v_ashrrev_i32_e32 v35, 31, v34
	global_store_dwordx2 v[32:33], v[60:61], off
	v_lshl_add_u64 v[34:35], v[34:35], 1, v[120:121]
	v_pk_mul_f32 v[36:37], v[36:37], v[56:57] op_sel_hi:[1,0]
	v_pk_mul_f32 v[38:39], v[38:39], v[56:57] op_sel_hi:[1,0]
	v_add_u32_e32 v58, 16, v92
	v_ashrrev_i32_e32 v59, 31, v58
	v_lshl_add_u64 v[58:59], v[58:59], 1, v[120:121]
	v_mfma_f32_32x32x16_bf16 v[16:31], v[130:133], v[146:149], v[16:31]
	s_waitcnt vmcnt(7)
	v_lshlrev_b32_e32 v60, 16, v156
	v_and_b32_e32 v61, 0xffff0000, v156
	v_lshlrev_b32_e32 v34, 16, v157
	v_and_b32_e32 v35, 0xffff0000, v157
	v_pk_mul_f32 v[36:37], v[36:37], v[60:61]
	v_pk_mul_f32 v[34:35], v[38:39], v[34:35]
	v_cvt_pk_bf16_f32 v36, v36, v37
	v_cvt_pk_bf16_f32 v37, v34, v35
	global_store_dwordx2 v[32:33], v[36:37], off offset:16
	v_pk_mul_f32 v[38:39], v[40:41], v[56:57] op_sel_hi:[1,0]
	v_pk_mul_f32 v[40:41], v[42:43], v[56:57] op_sel_hi:[1,0]
	v_add_u32_e32 v36, 24, v92
	v_ashrrev_i32_e32 v37, 31, v36
	v_lshl_add_u64 v[36:37], v[36:37], 1, v[120:121]
	v_mfma_f32_32x32x16_bf16 v[16:31], v[116:119], v[52:55], v[16:31]
	s_waitcnt vmcnt(7)
	v_lshlrev_b32_e32 v42, 16, v158
	v_and_b32_e32 v43, 0xffff0000, v158
	v_lshlrev_b32_e32 v34, 16, v159
	v_and_b32_e32 v35, 0xffff0000, v159
	v_pk_mul_f32 v[38:39], v[38:39], v[42:43]
	v_pk_mul_f32 v[34:35], v[40:41], v[34:35]
	v_cvt_pk_bf16_f32 v38, v38, v39
	v_cvt_pk_bf16_f32 v39, v34, v35
	global_store_dwordx2 v[32:33], v[38:39], off offset:32
	v_pk_mul_f32 v[38:39], v[44:45], v[56:57] op_sel_hi:[1,0]
	v_pk_mul_f32 v[40:41], v[46:47], v[56:57] op_sel_hi:[1,0]
	v_add_u32_e32 v36, 32, v92
	v_ashrrev_i32_e32 v37, 31, v36
	v_lshl_add_u64 v[36:37], v[36:37], 1, v[120:121]
	v_mfma_f32_32x32x16_bf16 v[16:31], v[88:91], v[48:51], v[16:31]
	s_waitcnt vmcnt(7)
	v_lshlrev_b32_e32 v42, 16, v160
	v_and_b32_e32 v43, 0xffff0000, v160
	v_lshlrev_b32_e32 v34, 16, v161
	v_and_b32_e32 v35, 0xffff0000, v161
	v_pk_mul_f32 v[38:39], v[38:39], v[42:43]
	v_pk_mul_f32 v[34:35], v[40:41], v[34:35]
	v_cvt_pk_bf16_f32 v38, v38, v39
	v_cvt_pk_bf16_f32 v39, v34, v35
	global_store_dwordx2 v[32:33], v[38:39], off offset:48
	v_mfma_f32_32x32x16_bf16 v[16:31], v[80:83], v[104:107], v[16:31]
	v_add_u32_e32 v36, 40, v92
	v_ashrrev_i32_e32 v37, 31, v36
	v_lshl_add_u64 v[36:37], v[36:37], 1, v[120:121]
	s_waitcnt vmcnt(7)
	v_lshlrev_b32_e32 v38, 16, v162
	s_nop 6
	v_pk_mul_f32 v[16:17], v[16:17], v[56:57] op_sel_hi:[1,0]
	v_pk_mul_f32 v[18:19], v[18:19], v[56:57] op_sel_hi:[1,0]
	v_and_b32_e32 v39, 0xffff0000, v162
	v_lshlrev_b32_e32 v34, 16, v163
	v_and_b32_e32 v35, 0xffff0000, v163
	v_pk_mul_f32 v[16:17], v[16:17], v[38:39]
	v_pk_mul_f32 v[18:19], v[18:19], v[34:35]
	v_cvt_pk_bf16_f32 v16, v16, v17
	v_cvt_pk_bf16_f32 v17, v18, v19
	global_store_dwordx2 v[32:33], v[16:17], off offset:64
	v_pk_mul_f32 v[20:21], v[20:21], v[56:57] op_sel_hi:[1,0]
	v_pk_mul_f32 v[22:23], v[22:23], v[56:57] op_sel_hi:[1,0]
	v_add_u32_e32 v18, 48, v92
	v_ashrrev_i32_e32 v19, 31, v18
	v_lshl_add_u64 v[18:19], v[18:19], 1, v[120:121]
	s_waitcnt vmcnt(7)
	v_lshlrev_b32_e32 v34, 16, v164
	v_and_b32_e32 v35, 0xffff0000, v164
	v_lshlrev_b32_e32 v16, 16, v165
	v_and_b32_e32 v17, 0xffff0000, v165
	v_pk_mul_f32 v[20:21], v[20:21], v[34:35]
	v_pk_mul_f32 v[16:17], v[22:23], v[16:17]
	v_cvt_pk_bf16_f32 v20, v20, v21
	v_cvt_pk_bf16_f32 v21, v16, v17
	global_store_dwordx2 v[32:33], v[20:21], off offset:80
	v_pk_mul_f32 v[20:21], v[24:25], v[56:57] op_sel_hi:[1,0]
	v_pk_mul_f32 v[22:23], v[26:27], v[56:57] op_sel_hi:[1,0]
	v_add_u32_e32 v18, 56, v92
	v_ashrrev_i32_e32 v19, 31, v18
	v_lshl_add_u64 v[18:19], v[18:19], 1, v[120:121]
	s_waitcnt vmcnt(7)
	v_lshlrev_b32_e32 v24, 16, v166
	v_and_b32_e32 v25, 0xffff0000, v166
	v_lshlrev_b32_e32 v16, 16, v167
	v_and_b32_e32 v17, 0xffff0000, v167
	v_pk_mul_f32 v[20:21], v[20:21], v[24:25]
	v_pk_mul_f32 v[16:17], v[22:23], v[16:17]
	v_cvt_pk_bf16_f32 v20, v20, v21
	v_cvt_pk_bf16_f32 v21, v16, v17
	global_store_dwordx2 v[32:33], v[20:21], off offset:96
	v_pk_mul_f32 v[18:19], v[28:29], v[56:57] op_sel_hi:[1,0]
	v_pk_mul_f32 v[20:21], v[30:31], v[56:57] op_sel_hi:[1,0]
	s_waitcnt vmcnt(7)
	v_lshlrev_b32_e32 v22, 16, v168
	v_and_b32_e32 v23, 0xffff0000, v168
	v_lshlrev_b32_e32 v16, 16, v169
	v_and_b32_e32 v17, 0xffff0000, v169
	v_pk_mul_f32 v[18:19], v[18:19], v[22:23]
	v_pk_mul_f32 v[16:17], v[20:21], v[16:17]
	v_cvt_pk_bf16_f32 v18, v18, v19
	v_cvt_pk_bf16_f32 v19, v16, v17
	global_store_dwordx2 v[32:33], v[18:19], off offset:112
	s_cbranch_scc1 .LBB0_643
